# GEMM K-loop headers aligned to 64 B
# speedup vs baseline: 1.0018x; 1.0018x over previous
.LBB0_384:
	s_and_b64 vcc, exec, s[0:1]
	s_cbranch_vccz .LBB0_272
	s_add_i32 s8, s40, s60
	s_cmpk_lt_i32 s8, 0x640
	s_mov_b64 s[0:1], -1
	s_cbranch_scc0 .LBB0_747
	s_ashr_i32 s4, s8, 5
	s_mul_hi_i32 s2, s4, 0x66666667
	s_lshr_b32 s3, s2, 31
	s_ashr_i32 s2, s2, 1
	s_add_i32 s5, s2, s3
	s_lshl_b32 s2, s8, 5
	s_lshl_b32 s34, s5, 10
	s_and_b32 s2, s2, 0x380
	s_or_b32 s3, s34, s2
	s_lshl_b32 s2, s8, 7
	s_and_b32 s33, s2, 0x180
	s_mul_i32 s2, s5, 5
	s_sub_i32 s2, s4, s2
	s_lshl_b32 s35, s2, 9
	s_or_b32 s33, s35, s33
	v_add_u32_e32 v0, s3, v93
	v_ashrrev_i32_e32 v1, 31, v0
	v_add_u32_e32 v2, s33, v93
	v_lshlrev_b64 v[0:1], 11, v[0:1]
	v_ashrrev_i32_e32 v3, 31, v2
	v_readlane_b32 s36, v242, 1
	v_lshl_add_u64 v[0:1], s[42:43], 0, v[0:1]
	v_lshlrev_b64 v[2:3], 11, v[2:3]
	v_readlane_b32 s38, v242, 3
	v_readlane_b32 s39, v242, 4
	v_mov_b32_e32 v107, v95
	v_readfirstlane_b32 s35, v114
	v_add_u32_e32 v8, 0x4000, v114
	v_lshl_add_u64 v[2:3], s[38:39], 0, v[2:3]
	v_lshl_add_u64 v[4:5], v[0:1], 0, v[106:107]
	s_mov_b32 m0, s35
	v_readfirstlane_b32 s35, v8
	v_mov_b32_e32 v109, v95
	v_add_u32_e32 v10, 0x400, v114
	s_waitcnt vmcnt(63) expcnt(7) lgkmcnt(15)
	s_barrier
	global_load_lds_dwordx4 v[4:5], off
	v_lshl_add_u64 v[6:7], v[2:3], 0, v[106:107]
	s_mov_b32 m0, s35
	v_lshl_add_u64 v[0:1], v[0:1], 0, v[108:109]
	v_readfirstlane_b32 s35, v10
	v_add_u32_e32 v10, 0x4400, v114
	global_load_lds_dwordx4 v[6:7], off
	v_lshl_add_u64 v[8:9], v[0:1], 0, s[10:11]
	s_mov_b32 m0, s35
	v_lshl_add_u64 v[2:3], v[2:3], 0, v[108:109]
	v_readfirstlane_b32 s35, v10
	global_load_lds_dwordx4 v[8:9], off
	v_lshl_add_u64 v[8:9], v[2:3], 0, s[10:11]
	s_mov_b32 m0, s35
	v_readlane_b32 s37, v242, 2
	global_load_lds_dwordx4 v[8:9], off
	v_add_u32_e32 v8, 0x800, v114
	s_mov_b64 s[36:37], 0x8000
	v_readfirstlane_b32 s35, v8
	v_lshl_add_u64 v[4:5], v[4:5], 0, s[36:37]
	s_mov_b32 m0, s35
	v_lshl_add_u64 v[0:1], v[0:1], 0, s[30:31]
	global_load_lds_dwordx4 v[4:5], off
	v_lshl_add_u64 v[4:5], v[6:7], 0, s[36:37]
	v_add_u32_e32 v6, 0x4800, v114
	s_and_b32 s0, s62, 0x380
	v_readfirstlane_b32 s35, v6
	s_mov_b32 m0, s35
	s_or_b32 s0, s0, s34
	global_load_lds_dwordx4 v[4:5], off
	v_add_u32_e32 v4, 0xc00, v114
	s_and_b32 s1, s24, 0x180
	v_readfirstlane_b32 s35, v4
	s_mov_b32 m0, s35
	s_mulk_i32 s5, 0xa00
	global_load_lds_dwordx4 v[0:1], off
	v_lshl_add_u64 v[0:1], v[2:3], 0, s[30:31]
	v_add_u32_e32 v2, 0x4c00, v114
	s_nop 0
	v_readfirstlane_b32 s35, v2
	s_mov_b32 m0, s35
	s_nop 0
	global_load_lds_dwordx4 v[0:1], off
	v_add_u32_e32 v0, s0, v93
	s_lshl_b32 s0, s4, 9
	s_or_b32 s0, s1, s0
	v_add_u32_e32 v2, s0, v93
	v_ashrrev_i32_e32 v1, 31, v0
	v_subrev_u32_e32 v2, s5, v2
	v_lshlrev_b64 v[0:1], 11, v[0:1]
	v_ashrrev_i32_e32 v3, 31, v2
	v_lshl_add_u64 v[64:65], v[102:103], 0, v[0:1]
	v_lshlrev_b64 v[2:3], 11, v[2:3]
	v_lshl_add_u64 v[68:69], v[104:105], 0, v[0:1]
	v_mov_b32_e32 v0, 0
	v_lshl_add_u64 v[66:67], v[102:103], 0, v[2:3]
	v_lshl_add_u64 v[70:71], v[104:105], 0, v[2:3]
	s_mov_b32 s4, 0
	s_mov_b64 s[0:1], 0
	v_mov_b32_e32 v1, v0
	v_mov_b32_e32 v2, v0
	v_mov_b32_e32 v3, v0
	v_mov_b32_e32 v4, v0
	v_mov_b32_e32 v5, v0
	v_mov_b32_e32 v6, v0
	v_mov_b32_e32 v7, v0
	v_mov_b32_e32 v8, v0
	v_mov_b32_e32 v9, v0
	v_mov_b32_e32 v10, v0
	v_mov_b32_e32 v11, v0
	v_mov_b32_e32 v12, v0
	v_mov_b32_e32 v13, v0
	v_mov_b32_e32 v14, v0
	v_mov_b32_e32 v15, v0
	v_mov_b32_e32 v16, v0
	v_mov_b32_e32 v17, v0
	v_mov_b32_e32 v18, v0
	v_mov_b32_e32 v19, v0
	v_mov_b32_e32 v20, v0
	v_mov_b32_e32 v21, v0
	v_mov_b32_e32 v22, v0
	v_mov_b32_e32 v23, v0
	v_mov_b32_e32 v24, v0
	v_mov_b32_e32 v25, v0
	v_mov_b32_e32 v26, v0
	v_mov_b32_e32 v27, v0
	v_mov_b32_e32 v28, v0
	v_mov_b32_e32 v29, v0
	v_mov_b32_e32 v30, v0
	v_mov_b32_e32 v31, v0
	v_mov_b32_e32 v32, v0
	v_mov_b32_e32 v33, v0
	v_mov_b32_e32 v34, v0
	v_mov_b32_e32 v35, v0
	v_mov_b32_e32 v36, v0
	v_mov_b32_e32 v37, v0
	v_mov_b32_e32 v38, v0
	v_mov_b32_e32 v39, v0
	v_mov_b32_e32 v40, v0
	v_mov_b32_e32 v41, v0
	v_mov_b32_e32 v42, v0
	v_mov_b32_e32 v43, v0
	v_mov_b32_e32 v44, v0
	v_mov_b32_e32 v45, v0
	v_mov_b32_e32 v46, v0
	v_mov_b32_e32 v47, v0
	v_mov_b32_e32 v48, v0
	v_mov_b32_e32 v49, v0
	v_mov_b32_e32 v50, v0
	v_mov_b32_e32 v51, v0
	v_mov_b32_e32 v52, v0
	v_mov_b32_e32 v53, v0
	v_mov_b32_e32 v54, v0
	v_mov_b32_e32 v55, v0
	v_mov_b32_e32 v56, v0
	v_mov_b32_e32 v57, v0
	v_mov_b32_e32 v58, v0
	v_mov_b32_e32 v59, v0
	v_mov_b32_e32 v60, v0
	v_mov_b32_e32 v61, v0
	v_mov_b32_e32 v62, v0
	v_mov_b32_e32 v63, v0
	.p2align 6

.LBB0_1087:
	s_add_i32 s2, s4, s5
	s_cmpk_gt_i32 s2, 0x1ff
	s_cbranch_scc1 .LBB0_1086
	s_ashr_i32 s0, s2, 31
	s_lshr_b32 s0, s0, 29
	s_add_i32 s0, s2, s0
	s_ashr_i32 s3, s0, 3
	s_mul_i32 s1, s3, 0xa0
	v_or_b32_e32 v0, s1, v134
	v_ashrrev_i32_e32 v1, 31, v0
	v_lshlrev_b64 v[0:1], 11, v[0:1]
	v_lshl_add_u64 v[2:3], s[42:43], 0, v[0:1]
	v_add_u32_e32 v8, v139, v144
	v_lshl_add_u64 v[6:7], v[84:85], 1, v[2:3]
	v_readfirstlane_b32 s6, v8
	v_lshl_add_u64 v[6:7], v[6:7], 0, v[80:81]
	s_mov_b32 m0, s6
	v_add_u32_e32 v8, v139, v145
	s_barrier
	global_load_lds_dwordx4 v[6:7], off
	v_lshl_add_u64 v[6:7], v[86:87], 1, v[2:3]
	v_mov_b32_e32 v109, v81
	v_readfirstlane_b32 s6, v8
	v_lshl_add_u64 v[6:7], v[6:7], 0, v[108:109]
	s_mov_b32 m0, s6
	v_add_u32_e32 v8, v139, v146
	global_load_lds_dwordx4 v[6:7], off
	v_lshl_add_u64 v[6:7], v[88:89], 1, v[2:3]
	v_mov_b32_e32 v111, v81
	v_readfirstlane_b32 s6, v8
	v_lshl_add_u64 v[6:7], v[6:7], 0, v[110:111]
	s_mov_b32 m0, s6
	v_add_u32_e32 v8, v139, v147
	s_and_b32 s0, s0, 0x1fffff8
	global_load_lds_dwordx4 v[6:7], off
	v_lshl_add_u64 v[6:7], v[90:91], 1, v[2:3]
	v_mov_b32_e32 v113, v81
	v_readfirstlane_b32 s6, v8
	s_sub_i32 s0, s2, s0
	v_lshl_add_u64 v[6:7], v[6:7], 0, v[112:113]
	s_mov_b32 m0, s6
	s_lshl_b32 s0, s0, 7
	global_load_lds_dwordx4 v[6:7], off
	v_add_u32_e32 v6, v139, v148
	v_add_u32_e32 v4, s0, v135
	v_lshl_add_u64 v[2:3], v[92:93], 1, v[2:3]
	v_mov_b32_e32 v115, v81
	v_readfirstlane_b32 s6, v6
	v_ashrrev_i32_e32 v5, 31, v4
	v_lshl_add_u64 v[2:3], v[2:3], 0, v[114:115]
	s_mov_b32 m0, s6
	v_add_u32_e32 v6, 0x5000, v152
	global_load_lds_dwordx4 v[2:3], off
	v_lshlrev_b64 v[2:3], 11, v[4:5]
	v_lshl_add_u64 v[2:3], s[58:59], 0, v[2:3]
	v_mov_b32_e32 v117, v81
	v_readfirstlane_b32 s6, v6
	v_mov_b32_e32 v119, v81
	v_lshl_add_u64 v[4:5], v[2:3], 0, v[116:117]
	s_mov_b32 m0, s6
	v_lshl_add_u64 v[2:3], v[2:3], 0, v[118:119]
	s_mov_b64 s[6:7], 0x4000
	v_add_u32_e32 v8, 0x5400, v152
	v_lshl_add_u64 v[6:7], v[2:3], 0, s[6:7]
	v_readfirstlane_b32 s6, v8
	global_load_lds_dwordx4 v[4:5], off
	s_mov_b32 m0, s6
	s_mov_b64 s[6:7], 0x8000
	global_load_lds_dwordx4 v[6:7], off
	v_add_u32_e32 v6, 0x5800, v152
	v_lshl_add_u64 v[4:5], v[4:5], 0, s[6:7]
	v_readfirstlane_b32 s6, v6
	s_mov_b32 m0, s6
	s_mov_b64 s[6:7], 0xc000
	global_load_lds_dwordx4 v[4:5], off
	v_add_u32_e32 v4, 0x5c00, v152
	v_lshl_add_u64 v[2:3], v[2:3], 0, s[6:7]
	v_readfirstlane_b32 s6, v4
	s_mov_b32 m0, s6
	v_lshl_add_u64 v[120:121], v[94:95], 0, v[0:1]
	global_load_lds_dwordx4 v[2:3], off
	v_lshl_add_u64 v[122:123], v[96:97], 0, v[0:1]
	v_lshl_add_u64 v[124:125], v[98:99], 0, v[0:1]
	v_lshl_add_u64 v[126:127], v[100:101], 0, v[0:1]
	v_lshl_add_u64 v[128:129], v[102:103], 0, v[0:1]
	v_lshl_add_u32 v0, s2, 7, v135
	s_lshl_b32 s2, s3, 10
	v_subrev_u32_e32 v0, s2, v0
	v_ashrrev_i32_e32 v1, 31, v0
	v_lshlrev_b64 v[0:1], 11, v[0:1]
	v_lshl_add_u64 v[130:131], v[104:105], 0, v[0:1]
	v_lshl_add_u64 v[132:133], v[106:107], 0, v[0:1]
	v_mov_b32_e32 v0, 0
	s_mov_b32 s6, 0
	s_mov_b64 s[2:3], 0
	v_mov_b32_e32 v1, v0
	v_mov_b32_e32 v2, v0
	v_mov_b32_e32 v3, v0
	v_mov_b32_e32 v4, v0
	v_mov_b32_e32 v5, v0
	v_mov_b32_e32 v6, v0
	v_mov_b32_e32 v7, v0
	v_mov_b32_e32 v8, v0
	v_mov_b32_e32 v9, v0
	v_mov_b32_e32 v10, v0
	v_mov_b32_e32 v11, v0
	v_mov_b32_e32 v12, v0
	v_mov_b32_e32 v13, v0
	v_mov_b32_e32 v14, v0
	v_mov_b32_e32 v15, v0
	v_mov_b32_e32 v16, v0
	v_mov_b32_e32 v17, v0
	v_mov_b32_e32 v18, v0
	v_mov_b32_e32 v19, v0
	v_mov_b32_e32 v20, v0
	v_mov_b32_e32 v21, v0
	v_mov_b32_e32 v22, v0
	v_mov_b32_e32 v23, v0
	v_mov_b32_e32 v24, v0
	v_mov_b32_e32 v25, v0
	v_mov_b32_e32 v26, v0
	v_mov_b32_e32 v27, v0
	v_mov_b32_e32 v28, v0
	v_mov_b32_e32 v29, v0
	v_mov_b32_e32 v30, v0
	v_mov_b32_e32 v31, v0
	v_mov_b32_e32 v32, v0
	v_mov_b32_e32 v33, v0
	v_mov_b32_e32 v34, v0
	v_mov_b32_e32 v35, v0
	v_mov_b32_e32 v36, v0
	v_mov_b32_e32 v37, v0
	v_mov_b32_e32 v38, v0
	v_mov_b32_e32 v39, v0
	v_mov_b32_e32 v40, v0
	v_mov_b32_e32 v41, v0
	v_mov_b32_e32 v42, v0
	v_mov_b32_e32 v43, v0
	v_mov_b32_e32 v44, v0
	v_mov_b32_e32 v45, v0
	v_mov_b32_e32 v46, v0
	v_mov_b32_e32 v47, v0
	v_mov_b32_e32 v48, v0
	v_mov_b32_e32 v49, v0
	v_mov_b32_e32 v50, v0
	v_mov_b32_e32 v51, v0
	v_mov_b32_e32 v52, v0
	v_mov_b32_e32 v53, v0
	v_mov_b32_e32 v54, v0
	v_mov_b32_e32 v55, v0
	v_mov_b32_e32 v56, v0
	v_mov_b32_e32 v57, v0
	v_mov_b32_e32 v58, v0
	v_mov_b32_e32 v59, v0
	v_mov_b32_e32 v60, v0
	v_mov_b32_e32 v61, v0
	v_mov_b32_e32 v62, v0
	v_mov_b32_e32 v63, v0
	v_mov_b32_e32 v64, v0
	v_mov_b32_e32 v65, v0
	v_mov_b32_e32 v66, v0
	v_mov_b32_e32 v67, v0
	v_mov_b32_e32 v68, v0
	v_mov_b32_e32 v69, v0
	v_mov_b32_e32 v70, v0
	v_mov_b32_e32 v71, v0
	v_mov_b32_e32 v72, v0
	v_mov_b32_e32 v73, v0
	v_mov_b32_e32 v74, v0
	v_mov_b32_e32 v75, v0
	v_mov_b32_e32 v76, v0
	v_mov_b32_e32 v77, v0
	v_mov_b32_e32 v78, v0
	v_mov_b32_e32 v79, v0
	.p2align 6

.LBB0_1203:
	s_add_i32 s6, s8, s9
	s_cmpk_gt_i32 s6, 0xdbf
	s_cbranch_scc1 .LBB0_1202
	s_ashr_i32 s16, s6, 5
	s_mul_hi_i32 s13, s16, 0x2e8ba2e9
	s_lshr_b32 s14, s13, 31
	s_ashr_i32 s13, s13, 1
	s_add_i32 s17, s13, s14
	s_lshl_b32 s13, s6, 5
	s_mul_i32 s14, s17, 11
	s_lshl_b32 s18, s17, 10
	s_and_b32 s13, s13, 0x380
	s_lshl_b32 s6, s6, 7
	s_sub_i32 s14, s16, s14
	s_or_b32 s13, s18, s13
	s_and_b32 s6, s6, 0x180
	s_lshl_b32 s14, s14, 9
	s_or_b32 s14, s14, s6
	v_add_u32_e32 v0, s13, v82
	v_ashrrev_i32_e32 v1, 31, v0
	v_add_u32_e32 v2, s14, v82
	v_lshlrev_b64 v[0:1], 11, v[0:1]
	v_ashrrev_i32_e32 v3, 31, v2
	v_lshl_add_u64 v[0:1], s[42:43], 0, v[0:1]
	v_lshlrev_b64 v[2:3], 11, v[2:3]
	v_readfirstlane_b32 s6, v83
	v_lshl_add_u64 v[2:3], s[72:73], 0, v[2:3]
	v_lshl_add_u64 v[4:5], v[0:1], 0, v[64:65]
	s_mov_b32 m0, s6
	v_readfirstlane_b32 s6, v91
	v_mov_b32_e32 v73, v65
	s_barrier
	global_load_lds_dwordx4 v[4:5], off
	v_lshl_add_u64 v[6:7], v[2:3], 0, v[64:65]
	s_mov_b32 m0, s6
	v_lshl_add_u64 v[0:1], v[0:1], 0, v[72:73]
	v_readfirstlane_b32 s6, v92
	global_load_lds_dwordx4 v[6:7], off
	v_lshl_add_u64 v[8:9], v[0:1], 0, s[0:1]
	s_mov_b32 m0, s6
	v_lshl_add_u64 v[2:3], v[2:3], 0, v[72:73]
	v_readfirstlane_b32 s6, v93
	global_load_lds_dwordx4 v[8:9], off
	v_lshl_add_u64 v[8:9], v[2:3], 0, s[0:1]
	s_mov_b32 m0, s6
	v_readfirstlane_b32 s6, v94
	global_load_lds_dwordx4 v[8:9], off
	v_lshl_add_u64 v[4:5], v[4:5], 0, s[2:3]
	s_mov_b32 m0, s6
	v_readfirstlane_b32 s6, v95
	global_load_lds_dwordx4 v[4:5], off
	v_lshl_add_u64 v[4:5], v[6:7], 0, s[2:3]
	s_mov_b32 m0, s6
	v_readfirstlane_b32 s6, v96
	global_load_lds_dwordx4 v[4:5], off
	v_lshl_add_u64 v[0:1], v[0:1], 0, s[4:5]
	s_mov_b32 m0, s6
	v_readfirstlane_b32 s6, v97
	global_load_lds_dwordx4 v[0:1], off
	v_lshl_add_u64 v[0:1], v[2:3], 0, s[4:5]
	s_mov_b32 m0, s6
	s_and_b32 s7, s10, 0x380
	global_load_lds_dwordx4 v[0:1], off
	s_or_b32 s6, s7, s18
	s_and_b32 s15, s11, 0x180
	v_add_u32_e32 v0, s6, v82
	s_lshl_b32 s6, s16, 9
	s_or_b32 s6, s15, s6
	v_add_u32_e32 v2, s6, v82
	s_mulk_i32 s17, 0x1600
	v_ashrrev_i32_e32 v1, 31, v0
	v_subrev_u32_e32 v2, s17, v2
	v_lshlrev_b64 v[0:1], 11, v[0:1]
	v_ashrrev_i32_e32 v3, 31, v2
	v_lshl_add_u64 v[74:75], v[68:69], 0, v[0:1]
	v_lshlrev_b64 v[2:3], 11, v[2:3]
	v_lshl_add_u64 v[78:79], v[70:71], 0, v[0:1]
	v_mov_b32_e32 v0, 0
	v_lshl_add_u64 v[76:77], v[68:69], 0, v[2:3]
	v_lshl_add_u64 v[80:81], v[70:71], 0, v[2:3]
	s_mov_b32 s15, 0
	s_mov_b64 s[6:7], 0
	v_mov_b32_e32 v1, v0
	v_mov_b32_e32 v2, v0
	v_mov_b32_e32 v3, v0
	v_mov_b32_e32 v4, v0
	v_mov_b32_e32 v5, v0
	v_mov_b32_e32 v6, v0
	v_mov_b32_e32 v7, v0
	v_mov_b32_e32 v8, v0
	v_mov_b32_e32 v9, v0
	v_mov_b32_e32 v10, v0
	v_mov_b32_e32 v11, v0
	v_mov_b32_e32 v12, v0
	v_mov_b32_e32 v13, v0
	v_mov_b32_e32 v14, v0
	v_mov_b32_e32 v15, v0
	v_mov_b32_e32 v16, v0
	v_mov_b32_e32 v17, v0
	v_mov_b32_e32 v18, v0
	v_mov_b32_e32 v19, v0
	v_mov_b32_e32 v20, v0
	v_mov_b32_e32 v21, v0
	v_mov_b32_e32 v22, v0
	v_mov_b32_e32 v23, v0
	v_mov_b32_e32 v24, v0
	v_mov_b32_e32 v25, v0
	v_mov_b32_e32 v26, v0
	v_mov_b32_e32 v27, v0
	v_mov_b32_e32 v28, v0
	v_mov_b32_e32 v29, v0
	v_mov_b32_e32 v30, v0
	v_mov_b32_e32 v31, v0
	v_mov_b32_e32 v32, v0
	v_mov_b32_e32 v33, v0
	v_mov_b32_e32 v34, v0
	v_mov_b32_e32 v35, v0
	v_mov_b32_e32 v36, v0
	v_mov_b32_e32 v37, v0
	v_mov_b32_e32 v38, v0
	v_mov_b32_e32 v39, v0
	v_mov_b32_e32 v40, v0
	v_mov_b32_e32 v41, v0
	v_mov_b32_e32 v42, v0
	v_mov_b32_e32 v43, v0
	v_mov_b32_e32 v44, v0
	v_mov_b32_e32 v45, v0
	v_mov_b32_e32 v46, v0
	v_mov_b32_e32 v47, v0
	v_mov_b32_e32 v48, v0
	v_mov_b32_e32 v49, v0
	v_mov_b32_e32 v50, v0
	v_mov_b32_e32 v51, v0
	v_mov_b32_e32 v52, v0
	v_mov_b32_e32 v53, v0
	v_mov_b32_e32 v54, v0
	v_mov_b32_e32 v55, v0
	v_mov_b32_e32 v56, v0
	v_mov_b32_e32 v57, v0
	v_mov_b32_e32 v58, v0
	v_mov_b32_e32 v59, v0
	v_mov_b32_e32 v60, v0
	v_mov_b32_e32 v61, v0
	v_mov_b32_e32 v62, v0
	v_mov_b32_e32 v63, v0
	.p2align 6

.LBB0_1261:
	s_add_i32 s2, s4, s5
	s_cmpk_gt_i32 s2, 0x1ff
	s_cbranch_scc1 .LBB0_1260
	s_ashr_i32 s0, s2, 31
	s_lshr_b32 s0, s0, 29
	s_add_i32 s0, s2, s0
	s_ashr_i32 s3, s0, 3
	s_mul_i32 s1, s3, 0xa0
	v_or_b32_e32 v6, s1, v134
	v_mov_b64_e32 v[0:1], s[52:53]
	v_mad_i64_i32 v[0:1], s[8:9], v6, s6, v[0:1]
	v_add_u32_e32 v5, v139, v144
	v_lshl_add_u64 v[2:3], v[84:85], 1, v[0:1]
	v_readfirstlane_b32 s7, v5
	v_lshl_add_u64 v[2:3], v[2:3], 0, v[80:81]
	s_mov_b32 m0, s7
	v_add_u32_e32 v5, v139, v145
	s_barrier
	global_load_lds_dwordx4 v[2:3], off
	v_lshl_add_u64 v[2:3], v[86:87], 1, v[0:1]
	v_mov_b32_e32 v109, v81
	v_readfirstlane_b32 s7, v5
	v_lshl_add_u64 v[2:3], v[2:3], 0, v[108:109]
	s_mov_b32 m0, s7
	v_add_u32_e32 v5, v139, v146
	global_load_lds_dwordx4 v[2:3], off
	v_lshl_add_u64 v[2:3], v[88:89], 1, v[0:1]
	v_mov_b32_e32 v111, v81
	v_readfirstlane_b32 s7, v5
	v_lshl_add_u64 v[2:3], v[2:3], 0, v[110:111]
	s_mov_b32 m0, s7
	v_add_u32_e32 v5, v139, v147
	global_load_lds_dwordx4 v[2:3], off
	v_lshl_add_u64 v[2:3], v[90:91], 1, v[0:1]
	v_mov_b32_e32 v113, v81
	v_readfirstlane_b32 s7, v5
	v_lshl_add_u64 v[2:3], v[2:3], 0, v[112:113]
	s_mov_b32 m0, s7
	s_and_b32 s0, s0, 0x1fffff8
	global_load_lds_dwordx4 v[2:3], off
	v_add_u32_e32 v2, v139, v148
	s_sub_i32 s0, s2, s0
	v_lshl_add_u64 v[0:1], v[92:93], 1, v[0:1]
	v_mov_b32_e32 v115, v81
	v_readfirstlane_b32 s7, v2
	s_lshl_b32 s0, s0, 7
	v_lshl_add_u64 v[0:1], v[0:1], 0, v[114:115]
	s_mov_b32 m0, s7
	v_add_u32_e32 v4, s0, v135
	global_load_lds_dwordx4 v[0:1], off
	v_mov_b64_e32 v[0:1], s[46:47]
	v_mad_i64_i32 v[0:1], s[8:9], v4, s6, v[0:1]
	v_add_u32_e32 v4, 0x5000, v152
	v_mov_b32_e32 v117, v81
	v_readfirstlane_b32 s7, v4
	v_mov_b32_e32 v119, v81
	v_add_u32_e32 v7, 0x5400, v152
	v_lshl_add_u64 v[2:3], v[0:1], 0, v[116:117]
	s_mov_b32 m0, s7
	v_lshl_add_u64 v[0:1], v[0:1], 0, v[118:119]
	s_mov_b64 s[8:9], 0xb000
	v_readfirstlane_b32 s7, v7
	global_load_lds_dwordx4 v[2:3], off
	v_lshl_add_u64 v[4:5], v[0:1], 0, s[8:9]
	s_mov_b32 m0, s7
	s_mov_b64 s[8:9], 0x16000
	global_load_lds_dwordx4 v[4:5], off
	v_add_u32_e32 v4, 0x5800, v152
	v_lshl_add_u64 v[2:3], v[2:3], 0, s[8:9]
	v_readfirstlane_b32 s7, v4
	s_mov_b32 m0, s7
	s_mov_b64 s[8:9], 0x21000
	global_load_lds_dwordx4 v[2:3], off
	v_add_u32_e32 v2, 0x5c00, v152
	v_lshl_add_u64 v[0:1], v[0:1], 0, s[8:9]
	v_readfirstlane_b32 s7, v2
	s_mov_b32 m0, s7
	v_mad_i64_i32 v[120:121], s[8:9], v6, s6, v[94:95]
	global_load_lds_dwordx4 v[0:1], off
	v_lshl_add_u32 v0, s2, 7, v135
	s_lshl_b32 s2, s3, 10
	v_subrev_u32_e32 v0, s2, v0
	v_mad_i64_i32 v[130:131], s[2:3], v0, s6, v[104:105]
	v_mad_i64_i32 v[132:133], s[2:3], v0, s6, v[106:107]
	v_mov_b32_e32 v0, 0
	v_mad_i64_i32 v[122:123], s[8:9], v6, s6, v[96:97]
	v_mad_i64_i32 v[124:125], s[8:9], v6, s6, v[98:99]
	v_mad_i64_i32 v[126:127], s[8:9], v6, s6, v[100:101]
	v_mad_i64_i32 v[128:129], s[8:9], v6, s6, v[102:103]
	s_mov_b32 s7, 0
	s_mov_b64 s[2:3], 0
	v_mov_b32_e32 v1, v0
	v_mov_b32_e32 v2, v0
	v_mov_b32_e32 v3, v0
	v_mov_b32_e32 v4, v0
	v_mov_b32_e32 v5, v0
	v_mov_b32_e32 v6, v0
	v_mov_b32_e32 v7, v0
	v_mov_b32_e32 v8, v0
	v_mov_b32_e32 v9, v0
	v_mov_b32_e32 v10, v0
	v_mov_b32_e32 v11, v0
	v_mov_b32_e32 v12, v0
	v_mov_b32_e32 v13, v0
	v_mov_b32_e32 v14, v0
	v_mov_b32_e32 v15, v0
	v_mov_b32_e32 v16, v0
	v_mov_b32_e32 v17, v0
	v_mov_b32_e32 v18, v0
	v_mov_b32_e32 v19, v0
	v_mov_b32_e32 v20, v0
	v_mov_b32_e32 v21, v0
	v_mov_b32_e32 v22, v0
	v_mov_b32_e32 v23, v0
	v_mov_b32_e32 v24, v0
	v_mov_b32_e32 v25, v0
	v_mov_b32_e32 v26, v0
	v_mov_b32_e32 v27, v0
	v_mov_b32_e32 v28, v0
	v_mov_b32_e32 v29, v0
	v_mov_b32_e32 v30, v0
	v_mov_b32_e32 v31, v0
	v_mov_b32_e32 v32, v0
	v_mov_b32_e32 v33, v0
	v_mov_b32_e32 v34, v0
	v_mov_b32_e32 v35, v0
	v_mov_b32_e32 v36, v0
	v_mov_b32_e32 v37, v0
	v_mov_b32_e32 v38, v0
	v_mov_b32_e32 v39, v0
	v_mov_b32_e32 v40, v0
	v_mov_b32_e32 v41, v0
	v_mov_b32_e32 v42, v0
	v_mov_b32_e32 v43, v0
	v_mov_b32_e32 v44, v0
	v_mov_b32_e32 v45, v0
	v_mov_b32_e32 v46, v0
	v_mov_b32_e32 v47, v0
	v_mov_b32_e32 v48, v0
	v_mov_b32_e32 v49, v0
	v_mov_b32_e32 v50, v0
	v_mov_b32_e32 v51, v0
	v_mov_b32_e32 v52, v0
	v_mov_b32_e32 v53, v0
	v_mov_b32_e32 v54, v0
	v_mov_b32_e32 v55, v0
	v_mov_b32_e32 v56, v0
	v_mov_b32_e32 v57, v0
	v_mov_b32_e32 v58, v0
	v_mov_b32_e32 v59, v0
	v_mov_b32_e32 v60, v0
	v_mov_b32_e32 v61, v0
	v_mov_b32_e32 v62, v0
	v_mov_b32_e32 v63, v0
	v_mov_b32_e32 v64, v0
	v_mov_b32_e32 v65, v0
	v_mov_b32_e32 v66, v0
	v_mov_b32_e32 v67, v0
	v_mov_b32_e32 v68, v0
	v_mov_b32_e32 v69, v0
	v_mov_b32_e32 v70, v0
	v_mov_b32_e32 v71, v0
	v_mov_b32_e32 v72, v0
	v_mov_b32_e32 v73, v0
	v_mov_b32_e32 v74, v0
	v_mov_b32_e32 v75, v0
	v_mov_b32_e32 v76, v0
	v_mov_b32_e32 v77, v0
	v_mov_b32_e32 v78, v0
	v_mov_b32_e32 v79, v0
	.p2align 6

.LBB0_1484:
	s_and_b64 vcc, exec, s[0:1]
	s_cbranch_vccz .LBB0_1377
	s_add_i32 s33, s33, s40
	s_cmpk_gt_i32 s33, 0x63f
	s_cbranch_scc1 .LBB0_1377
	s_ashr_i32 s4, s33, 5
	s_mul_hi_i32 s2, s4, 0x66666667
	s_lshr_b32 s3, s2, 31
	s_ashr_i32 s2, s2, 1
	s_add_i32 s5, s2, s3
	s_lshl_b32 s2, s33, 5
	s_lshl_b32 s36, s5, 10
	s_and_b32 s2, s2, 0x380
	s_or_b32 s3, s36, s2
	s_lshl_b32 s2, s33, 7
	s_and_b32 s8, s2, 0x180
	s_mul_i32 s2, s5, 5
	s_sub_i32 s2, s4, s2
	s_lshl_b32 s33, s2, 9
	s_or_b32 s8, s33, s8
	v_add_u32_e32 v0, s3, v93
	v_ashrrev_i32_e32 v1, 31, v0
	v_add_u32_e32 v2, s8, v93
	v_lshlrev_b64 v[0:1], 11, v[0:1]
	v_ashrrev_i32_e32 v3, 31, v2
	v_lshl_add_u64 v[0:1], s[42:43], 0, v[0:1]
	v_lshlrev_b64 v[2:3], 11, v[2:3]
	v_mov_b32_e32 v107, v95
	v_readfirstlane_b32 s33, v114
	v_add_u32_e32 v8, 0x4000, v114
	v_lshl_add_u64 v[2:3], s[6:7], 0, v[2:3]
	v_lshl_add_u64 v[4:5], v[0:1], 0, v[106:107]
	s_mov_b32 m0, s33
	v_readfirstlane_b32 s33, v8
	v_mov_b32_e32 v109, v95
	v_add_u32_e32 v10, 0x400, v114
	s_waitcnt vmcnt(63) expcnt(7) lgkmcnt(15)
	s_barrier
	global_load_lds_dwordx4 v[4:5], off
	v_lshl_add_u64 v[6:7], v[2:3], 0, v[106:107]
	s_mov_b32 m0, s33
	v_lshl_add_u64 v[0:1], v[0:1], 0, v[108:109]
	v_readfirstlane_b32 s33, v10
	v_add_u32_e32 v10, 0x4400, v114
	global_load_lds_dwordx4 v[6:7], off
	v_lshl_add_u64 v[8:9], v[0:1], 0, s[10:11]
	s_mov_b32 m0, s33
	v_lshl_add_u64 v[2:3], v[2:3], 0, v[108:109]
	v_readfirstlane_b32 s33, v10
	global_load_lds_dwordx4 v[8:9], off
	v_lshl_add_u64 v[8:9], v[2:3], 0, s[10:11]
	s_mov_b32 m0, s33
	v_lshl_add_u64 v[4:5], v[4:5], 0, s[30:31]
	global_load_lds_dwordx4 v[8:9], off
	v_add_u32_e32 v8, 0x800, v114
	v_lshl_add_u64 v[0:1], v[0:1], 0, s[34:35]
	v_readfirstlane_b32 s33, v8
	s_mov_b32 m0, s33
	s_and_b32 s0, s77, 0x380
	global_load_lds_dwordx4 v[4:5], off
	v_lshl_add_u64 v[4:5], v[6:7], 0, s[30:31]
	v_add_u32_e32 v6, 0x4800, v114
	s_or_b32 s0, s0, s36
	v_readfirstlane_b32 s33, v6
	s_mov_b32 m0, s33
	s_and_b32 s1, s78, 0x180
	global_load_lds_dwordx4 v[4:5], off
	v_add_u32_e32 v4, 0xc00, v114
	s_mulk_i32 s5, 0xa00
	v_readfirstlane_b32 s33, v4
	s_mov_b32 m0, s33
	s_nop 0
	global_load_lds_dwordx4 v[0:1], off
	v_lshl_add_u64 v[0:1], v[2:3], 0, s[34:35]
	v_add_u32_e32 v2, 0x4c00, v114
	s_nop 0
	v_readfirstlane_b32 s33, v2
	s_mov_b32 m0, s33
	s_nop 0
	global_load_lds_dwordx4 v[0:1], off
	v_add_u32_e32 v0, s0, v93
	s_lshl_b32 s0, s4, 9
	s_or_b32 s0, s1, s0
	v_add_u32_e32 v2, s0, v93
	v_ashrrev_i32_e32 v1, 31, v0
	v_subrev_u32_e32 v2, s5, v2
	v_lshlrev_b64 v[0:1], 11, v[0:1]
	v_ashrrev_i32_e32 v3, 31, v2
	v_lshl_add_u64 v[64:65], v[102:103], 0, v[0:1]
	v_lshlrev_b64 v[2:3], 11, v[2:3]
	v_lshl_add_u64 v[68:69], v[104:105], 0, v[0:1]
	v_mov_b32_e32 v0, 0
	v_lshl_add_u64 v[66:67], v[102:103], 0, v[2:3]
	v_lshl_add_u64 v[70:71], v[104:105], 0, v[2:3]
	s_mov_b32 s4, 0
	s_mov_b64 s[0:1], 0
	v_mov_b32_e32 v1, v0
	v_mov_b32_e32 v2, v0
	v_mov_b32_e32 v3, v0
	v_mov_b32_e32 v4, v0
	v_mov_b32_e32 v5, v0
	v_mov_b32_e32 v6, v0
	v_mov_b32_e32 v7, v0
	v_mov_b32_e32 v8, v0
	v_mov_b32_e32 v9, v0
	v_mov_b32_e32 v10, v0
	v_mov_b32_e32 v11, v0
	v_mov_b32_e32 v12, v0
	v_mov_b32_e32 v13, v0
	v_mov_b32_e32 v14, v0
	v_mov_b32_e32 v15, v0
	v_mov_b32_e32 v16, v0
	v_mov_b32_e32 v17, v0
	v_mov_b32_e32 v18, v0
	v_mov_b32_e32 v19, v0
	v_mov_b32_e32 v20, v0
	v_mov_b32_e32 v21, v0
	v_mov_b32_e32 v22, v0
	v_mov_b32_e32 v23, v0
	v_mov_b32_e32 v24, v0
	v_mov_b32_e32 v25, v0
	v_mov_b32_e32 v26, v0
	v_mov_b32_e32 v27, v0
	v_mov_b32_e32 v28, v0
	v_mov_b32_e32 v29, v0
	v_mov_b32_e32 v30, v0
	v_mov_b32_e32 v31, v0
	v_mov_b32_e32 v32, v0
	v_mov_b32_e32 v33, v0
	v_mov_b32_e32 v34, v0
	v_mov_b32_e32 v35, v0
	v_mov_b32_e32 v36, v0
	v_mov_b32_e32 v37, v0
	v_mov_b32_e32 v38, v0
	v_mov_b32_e32 v39, v0
	v_mov_b32_e32 v40, v0
	v_mov_b32_e32 v41, v0
	v_mov_b32_e32 v42, v0
	v_mov_b32_e32 v43, v0
	v_mov_b32_e32 v44, v0
	v_mov_b32_e32 v45, v0
	v_mov_b32_e32 v46, v0
	v_mov_b32_e32 v47, v0
	v_mov_b32_e32 v48, v0
	v_mov_b32_e32 v49, v0
	v_mov_b32_e32 v50, v0
	v_mov_b32_e32 v51, v0
	v_mov_b32_e32 v52, v0
	v_mov_b32_e32 v53, v0
	v_mov_b32_e32 v54, v0
	v_mov_b32_e32 v55, v0
	v_mov_b32_e32 v56, v0
	v_mov_b32_e32 v57, v0
	v_mov_b32_e32 v58, v0
	v_mov_b32_e32 v59, v0
	v_mov_b32_e32 v60, v0
	v_mov_b32_e32 v61, v0
	v_mov_b32_e32 v62, v0
	v_mov_b32_e32 v63, v0
	.p2align 6

.LBB0_2085:
	s_add_i32 s16, s18, s19
	s_cmpk_gt_i32 s16, 0x1ff
	s_cbranch_scc1 .LBB0_2084
	s_ashr_i32 s14, s16, 31
	s_lshr_b32 s14, s14, 29
	s_add_i32 s14, s16, s14
	s_ashr_i32 s17, s14, 3
	s_mul_i32 s15, s17, 0xa0
	v_or_b32_e32 v0, s15, v134
	v_ashrrev_i32_e32 v1, 31, v0
	v_lshlrev_b64 v[0:1], 11, v[0:1]
	v_lshl_add_u64 v[2:3], s[42:43], 0, v[0:1]
	v_add_u32_e32 v8, v138, v143
	v_lshl_add_u64 v[6:7], v[84:85], 1, v[2:3]
	v_readfirstlane_b32 s20, v8
	v_lshl_add_u64 v[6:7], v[6:7], 0, v[80:81]
	s_mov_b32 m0, s20
	v_add_u32_e32 v8, v138, v144
	s_barrier
	global_load_lds_dwordx4 v[6:7], off
	v_lshl_add_u64 v[6:7], v[86:87], 1, v[2:3]
	v_mov_b32_e32 v109, v81
	v_readfirstlane_b32 s20, v8
	v_lshl_add_u64 v[6:7], v[6:7], 0, v[108:109]
	s_mov_b32 m0, s20
	v_add_u32_e32 v8, v138, v145
	global_load_lds_dwordx4 v[6:7], off
	v_lshl_add_u64 v[6:7], v[88:89], 1, v[2:3]
	v_mov_b32_e32 v111, v81
	v_readfirstlane_b32 s20, v8
	v_lshl_add_u64 v[6:7], v[6:7], 0, v[110:111]
	s_mov_b32 m0, s20
	v_add_u32_e32 v8, v138, v146
	s_and_b32 s14, s14, 0x1fffff8
	global_load_lds_dwordx4 v[6:7], off
	v_lshl_add_u64 v[6:7], v[90:91], 1, v[2:3]
	v_mov_b32_e32 v113, v81
	v_readfirstlane_b32 s20, v8
	s_sub_i32 s14, s16, s14
	v_lshl_add_u64 v[6:7], v[6:7], 0, v[112:113]
	s_mov_b32 m0, s20
	s_lshl_b32 s14, s14, 7
	global_load_lds_dwordx4 v[6:7], off
	v_add_u32_e32 v6, v138, v147
	v_add_u32_e32 v4, s14, v135
	v_lshl_add_u64 v[2:3], v[92:93], 1, v[2:3]
	v_mov_b32_e32 v115, v81
	v_readfirstlane_b32 s20, v6
	v_ashrrev_i32_e32 v5, 31, v4
	v_lshl_add_u64 v[2:3], v[2:3], 0, v[114:115]
	s_mov_b32 m0, s20
	v_add_u32_e32 v6, 0x5000, v151
	global_load_lds_dwordx4 v[2:3], off
	v_lshlrev_b64 v[2:3], 11, v[4:5]
	v_lshl_add_u64 v[2:3], s[92:93], 0, v[2:3]
	v_mov_b32_e32 v117, v81
	v_readfirstlane_b32 s20, v6
	v_mov_b32_e32 v119, v81
	v_add_u32_e32 v8, 0x5400, v151
	v_lshl_add_u64 v[4:5], v[2:3], 0, v[116:117]
	s_mov_b32 m0, s20
	v_lshl_add_u64 v[2:3], v[2:3], 0, v[118:119]
	v_readfirstlane_b32 s20, v8
	global_load_lds_dwordx4 v[4:5], off
	v_lshl_add_u64 v[6:7], v[2:3], 0, s[0:1]
	s_mov_b32 m0, s20
	v_lshl_add_u64 v[4:5], v[4:5], 0, s[2:3]
	global_load_lds_dwordx4 v[6:7], off
	v_add_u32_e32 v6, 0x5800, v151
	v_lshl_add_u64 v[2:3], v[2:3], 0, s[4:5]
	v_readfirstlane_b32 s20, v6
	s_mov_b32 m0, s20
	v_lshl_add_u64 v[120:121], v[94:95], 0, v[0:1]
	global_load_lds_dwordx4 v[4:5], off
	v_add_u32_e32 v4, 0x5c00, v151
	v_lshl_add_u64 v[122:123], v[96:97], 0, v[0:1]
	v_readfirstlane_b32 s20, v4
	s_mov_b32 m0, s20
	v_lshl_add_u64 v[124:125], v[98:99], 0, v[0:1]
	global_load_lds_dwordx4 v[2:3], off
	v_lshl_add_u64 v[126:127], v[100:101], 0, v[0:1]
	v_lshl_add_u64 v[128:129], v[102:103], 0, v[0:1]
	v_lshl_add_u32 v0, s16, 7, v135
	s_lshl_b32 s16, s17, 10
	v_subrev_u32_e32 v0, s16, v0
	v_ashrrev_i32_e32 v1, 31, v0
	v_lshlrev_b64 v[0:1], 11, v[0:1]
	v_lshl_add_u64 v[130:131], v[104:105], 0, v[0:1]
	v_lshl_add_u64 v[132:133], v[106:107], 0, v[0:1]
	v_mov_b32_e32 v0, 0
	s_mov_b32 s20, 0
	s_mov_b64 s[16:17], 0
	v_mov_b32_e32 v1, v0
	v_mov_b32_e32 v2, v0
	v_mov_b32_e32 v3, v0
	v_mov_b32_e32 v4, v0
	v_mov_b32_e32 v5, v0
	v_mov_b32_e32 v6, v0
	v_mov_b32_e32 v7, v0
	v_mov_b32_e32 v8, v0
	v_mov_b32_e32 v9, v0
	v_mov_b32_e32 v10, v0
	v_mov_b32_e32 v11, v0
	v_mov_b32_e32 v12, v0
	v_mov_b32_e32 v13, v0
	v_mov_b32_e32 v14, v0
	v_mov_b32_e32 v15, v0
	v_mov_b32_e32 v16, v0
	v_mov_b32_e32 v17, v0
	v_mov_b32_e32 v18, v0
	v_mov_b32_e32 v19, v0
	v_mov_b32_e32 v20, v0
	v_mov_b32_e32 v21, v0
	v_mov_b32_e32 v22, v0
	v_mov_b32_e32 v23, v0
	v_mov_b32_e32 v24, v0
	v_mov_b32_e32 v25, v0
	v_mov_b32_e32 v26, v0
	v_mov_b32_e32 v27, v0
	v_mov_b32_e32 v28, v0
	v_mov_b32_e32 v29, v0
	v_mov_b32_e32 v30, v0
	v_mov_b32_e32 v31, v0
	v_mov_b32_e32 v32, v0
	v_mov_b32_e32 v33, v0
	v_mov_b32_e32 v34, v0
	v_mov_b32_e32 v35, v0
	v_mov_b32_e32 v36, v0
	v_mov_b32_e32 v37, v0
	v_mov_b32_e32 v38, v0
	v_mov_b32_e32 v39, v0
	v_mov_b32_e32 v40, v0
	v_mov_b32_e32 v41, v0
	v_mov_b32_e32 v42, v0
	v_mov_b32_e32 v43, v0
	v_mov_b32_e32 v44, v0
	v_mov_b32_e32 v45, v0
	v_mov_b32_e32 v46, v0
	v_mov_b32_e32 v47, v0
	v_mov_b32_e32 v48, v0
	v_mov_b32_e32 v49, v0
	v_mov_b32_e32 v50, v0
	v_mov_b32_e32 v51, v0
	v_mov_b32_e32 v52, v0
	v_mov_b32_e32 v53, v0
	v_mov_b32_e32 v54, v0
	v_mov_b32_e32 v55, v0
	v_mov_b32_e32 v56, v0
	v_mov_b32_e32 v57, v0
	v_mov_b32_e32 v58, v0
	v_mov_b32_e32 v59, v0
	v_mov_b32_e32 v60, v0
	v_mov_b32_e32 v61, v0
	v_mov_b32_e32 v62, v0
	v_mov_b32_e32 v63, v0
	v_mov_b32_e32 v64, v0
	v_mov_b32_e32 v65, v0
	v_mov_b32_e32 v66, v0
	v_mov_b32_e32 v67, v0
	v_mov_b32_e32 v68, v0
	v_mov_b32_e32 v69, v0
	v_mov_b32_e32 v70, v0
	v_mov_b32_e32 v71, v0
	v_mov_b32_e32 v72, v0
	v_mov_b32_e32 v73, v0
	v_mov_b32_e32 v74, v0
	v_mov_b32_e32 v75, v0
	v_mov_b32_e32 v76, v0
	v_mov_b32_e32 v77, v0
	v_mov_b32_e32 v78, v0
	v_mov_b32_e32 v79, v0
	.p2align 6

.LBB0_2201:
	s_add_i32 s22, s24, s25
	s_cmpk_gt_i32 s22, 0xdbf
	s_cbranch_scc1 .LBB0_2200
	s_ashr_i32 s33, s22, 5
	s_mul_hi_i32 s29, s33, 0x2e8ba2e9
	s_lshr_b32 s30, s29, 31
	s_ashr_i32 s29, s29, 1
	s_add_i32 s34, s29, s30
	s_lshl_b32 s29, s22, 5
	s_mul_i32 s30, s34, 11
	s_lshl_b32 s35, s34, 10
	s_and_b32 s29, s29, 0x380
	s_lshl_b32 s22, s22, 7
	s_sub_i32 s30, s33, s30
	s_or_b32 s29, s35, s29
	s_and_b32 s22, s22, 0x180
	s_lshl_b32 s30, s30, 9
	s_or_b32 s30, s30, s22
	v_add_u32_e32 v0, s29, v82
	v_ashrrev_i32_e32 v1, 31, v0
	v_add_u32_e32 v2, s30, v82
	v_lshlrev_b64 v[0:1], 11, v[0:1]
	v_ashrrev_i32_e32 v3, 31, v2
	v_lshl_add_u64 v[0:1], s[42:43], 0, v[0:1]
	v_lshlrev_b64 v[2:3], 11, v[2:3]
	v_readfirstlane_b32 s22, v83
	v_lshl_add_u64 v[2:3], s[44:45], 0, v[2:3]
	v_lshl_add_u64 v[4:5], v[0:1], 0, v[64:65]
	s_mov_b32 m0, s22
	v_readfirstlane_b32 s22, v91
	v_mov_b32_e32 v73, v65
	s_barrier
	global_load_lds_dwordx4 v[4:5], off
	v_lshl_add_u64 v[6:7], v[2:3], 0, v[64:65]
	s_mov_b32 m0, s22
	v_lshl_add_u64 v[0:1], v[0:1], 0, v[72:73]
	v_readfirstlane_b32 s22, v92
	global_load_lds_dwordx4 v[6:7], off
	v_lshl_add_u64 v[8:9], v[0:1], 0, s[0:1]
	s_mov_b32 m0, s22
	v_lshl_add_u64 v[2:3], v[2:3], 0, v[72:73]
	v_readfirstlane_b32 s22, v93
	global_load_lds_dwordx4 v[8:9], off
	v_lshl_add_u64 v[8:9], v[2:3], 0, s[0:1]
	s_mov_b32 m0, s22
	v_readfirstlane_b32 s22, v94
	global_load_lds_dwordx4 v[8:9], off
	v_lshl_add_u64 v[4:5], v[4:5], 0, s[2:3]
	s_mov_b32 m0, s22
	v_readfirstlane_b32 s22, v95
	global_load_lds_dwordx4 v[4:5], off
	v_lshl_add_u64 v[4:5], v[6:7], 0, s[2:3]
	s_mov_b32 m0, s22
	v_readfirstlane_b32 s22, v96
	global_load_lds_dwordx4 v[4:5], off
	v_lshl_add_u64 v[0:1], v[0:1], 0, s[4:5]
	s_mov_b32 m0, s22
	v_readfirstlane_b32 s22, v97
	global_load_lds_dwordx4 v[0:1], off
	v_lshl_add_u64 v[0:1], v[2:3], 0, s[4:5]
	s_mov_b32 m0, s22
	s_and_b32 s23, s26, 0x380
	global_load_lds_dwordx4 v[0:1], off
	s_or_b32 s22, s23, s35
	s_and_b32 s31, s27, 0x180
	v_add_u32_e32 v0, s22, v82
	s_lshl_b32 s22, s33, 9
	s_or_b32 s22, s31, s22
	v_add_u32_e32 v2, s22, v82
	s_mulk_i32 s34, 0x1600
	v_ashrrev_i32_e32 v1, 31, v0
	v_subrev_u32_e32 v2, s34, v2
	v_lshlrev_b64 v[0:1], 11, v[0:1]
	v_ashrrev_i32_e32 v3, 31, v2
	v_lshl_add_u64 v[74:75], v[68:69], 0, v[0:1]
	v_lshlrev_b64 v[2:3], 11, v[2:3]
	v_lshl_add_u64 v[78:79], v[70:71], 0, v[0:1]
	v_mov_b32_e32 v0, 0
	v_lshl_add_u64 v[76:77], v[68:69], 0, v[2:3]
	v_lshl_add_u64 v[80:81], v[70:71], 0, v[2:3]
	s_mov_b32 s31, 0
	s_mov_b64 s[22:23], 0
	v_mov_b32_e32 v1, v0
	v_mov_b32_e32 v2, v0
	v_mov_b32_e32 v3, v0
	v_mov_b32_e32 v4, v0
	v_mov_b32_e32 v5, v0
	v_mov_b32_e32 v6, v0
	v_mov_b32_e32 v7, v0
	v_mov_b32_e32 v8, v0
	v_mov_b32_e32 v9, v0
	v_mov_b32_e32 v10, v0
	v_mov_b32_e32 v11, v0
	v_mov_b32_e32 v12, v0
	v_mov_b32_e32 v13, v0
	v_mov_b32_e32 v14, v0
	v_mov_b32_e32 v15, v0
	v_mov_b32_e32 v16, v0
	v_mov_b32_e32 v17, v0
	v_mov_b32_e32 v18, v0
	v_mov_b32_e32 v19, v0
	v_mov_b32_e32 v20, v0
	v_mov_b32_e32 v21, v0
	v_mov_b32_e32 v22, v0
	v_mov_b32_e32 v23, v0
	v_mov_b32_e32 v24, v0
	v_mov_b32_e32 v25, v0
	v_mov_b32_e32 v26, v0
	v_mov_b32_e32 v27, v0
	v_mov_b32_e32 v28, v0
	v_mov_b32_e32 v29, v0
	v_mov_b32_e32 v30, v0
	v_mov_b32_e32 v31, v0
	v_mov_b32_e32 v32, v0
	v_mov_b32_e32 v33, v0
	v_mov_b32_e32 v34, v0
	v_mov_b32_e32 v35, v0
	v_mov_b32_e32 v36, v0
	v_mov_b32_e32 v37, v0
	v_mov_b32_e32 v38, v0
	v_mov_b32_e32 v39, v0
	v_mov_b32_e32 v40, v0
	v_mov_b32_e32 v41, v0
	v_mov_b32_e32 v42, v0
	v_mov_b32_e32 v43, v0
	v_mov_b32_e32 v44, v0
	v_mov_b32_e32 v45, v0
	v_mov_b32_e32 v46, v0
	v_mov_b32_e32 v47, v0
	v_mov_b32_e32 v48, v0
	v_mov_b32_e32 v49, v0
	v_mov_b32_e32 v50, v0
	v_mov_b32_e32 v51, v0
	v_mov_b32_e32 v52, v0
	v_mov_b32_e32 v53, v0
	v_mov_b32_e32 v54, v0
	v_mov_b32_e32 v55, v0
	v_mov_b32_e32 v56, v0
	v_mov_b32_e32 v57, v0
	v_mov_b32_e32 v58, v0
	v_mov_b32_e32 v59, v0
	v_mov_b32_e32 v60, v0
	v_mov_b32_e32 v61, v0
	v_mov_b32_e32 v62, v0
	v_mov_b32_e32 v63, v0
	.p2align 6

.LBB0_2259:
	s_add_i32 s16, s18, s19
	s_cmpk_gt_i32 s16, 0x1ff
	s_cbranch_scc1 .LBB0_2258
	s_ashr_i32 s14, s16, 31
	s_lshr_b32 s14, s14, 29
	s_add_i32 s14, s16, s14
	s_ashr_i32 s17, s14, 3
	s_mul_i32 s15, s17, 0xa0
	v_or_b32_e32 v6, s15, v134
	v_mov_b64_e32 v[0:1], s[52:53]
	v_mad_i64_i32 v[0:1], s[22:23], v6, s20, v[0:1]
	v_add_u32_e32 v5, v138, v143
	v_lshl_add_u64 v[2:3], v[84:85], 1, v[0:1]
	v_readfirstlane_b32 s21, v5
	v_lshl_add_u64 v[2:3], v[2:3], 0, v[80:81]
	s_mov_b32 m0, s21
	v_add_u32_e32 v5, v138, v144
	s_barrier
	global_load_lds_dwordx4 v[2:3], off
	v_lshl_add_u64 v[2:3], v[86:87], 1, v[0:1]
	v_mov_b32_e32 v109, v81
	v_readfirstlane_b32 s21, v5
	v_lshl_add_u64 v[2:3], v[2:3], 0, v[108:109]
	s_mov_b32 m0, s21
	v_add_u32_e32 v5, v138, v145
	global_load_lds_dwordx4 v[2:3], off
	v_lshl_add_u64 v[2:3], v[88:89], 1, v[0:1]
	v_mov_b32_e32 v111, v81
	v_readfirstlane_b32 s21, v5
	v_lshl_add_u64 v[2:3], v[2:3], 0, v[110:111]
	s_mov_b32 m0, s21
	v_add_u32_e32 v5, v138, v146
	global_load_lds_dwordx4 v[2:3], off
	v_lshl_add_u64 v[2:3], v[90:91], 1, v[0:1]
	v_mov_b32_e32 v113, v81
	v_readfirstlane_b32 s21, v5
	v_lshl_add_u64 v[2:3], v[2:3], 0, v[112:113]
	s_mov_b32 m0, s21
	s_and_b32 s14, s14, 0x1fffff8
	global_load_lds_dwordx4 v[2:3], off
	v_add_u32_e32 v2, v138, v147
	s_sub_i32 s14, s16, s14
	v_lshl_add_u64 v[0:1], v[92:93], 1, v[0:1]
	v_mov_b32_e32 v115, v81
	v_readfirstlane_b32 s21, v2
	v_readlane_b32 s22, v241, 25
	s_lshl_b32 s14, s14, 7
	v_lshl_add_u64 v[0:1], v[0:1], 0, v[114:115]
	s_mov_b32 m0, s21
	v_readlane_b32 s23, v241, 26
	v_add_u32_e32 v4, s14, v135
	global_load_lds_dwordx4 v[0:1], off
	v_mov_b64_e32 v[0:1], s[22:23]
	v_mad_i64_i32 v[0:1], s[22:23], v4, s20, v[0:1]
	v_add_u32_e32 v4, 0x5000, v151
	v_mov_b32_e32 v117, v81
	v_readfirstlane_b32 s21, v4
	v_mov_b32_e32 v119, v81
	v_add_u32_e32 v7, 0x5400, v151
	v_lshl_add_u64 v[2:3], v[0:1], 0, v[116:117]
	s_mov_b32 m0, s21
	v_lshl_add_u64 v[0:1], v[0:1], 0, v[118:119]
	v_readfirstlane_b32 s21, v7
	global_load_lds_dwordx4 v[2:3], off
	v_lshl_add_u64 v[4:5], v[0:1], 0, s[0:1]
	s_mov_b32 m0, s21
	v_lshl_add_u64 v[2:3], v[2:3], 0, s[2:3]
	global_load_lds_dwordx4 v[4:5], off
	v_add_u32_e32 v4, 0x5800, v151
	v_lshl_add_u64 v[0:1], v[0:1], 0, s[4:5]
	v_readfirstlane_b32 s21, v4
	s_mov_b32 m0, s21
	v_mad_i64_i32 v[120:121], s[22:23], v6, s20, v[94:95]
	global_load_lds_dwordx4 v[2:3], off
	v_add_u32_e32 v2, 0x5c00, v151
	v_mad_i64_i32 v[122:123], s[22:23], v6, s20, v[96:97]
	v_readfirstlane_b32 s21, v2
	s_mov_b32 m0, s21
	v_mad_i64_i32 v[124:125], s[22:23], v6, s20, v[98:99]
	global_load_lds_dwordx4 v[0:1], off
	v_lshl_add_u32 v0, s16, 7, v135
	s_lshl_b32 s16, s17, 10
	v_subrev_u32_e32 v0, s16, v0
	v_mad_i64_i32 v[130:131], s[16:17], v0, s20, v[104:105]
	v_mad_i64_i32 v[132:133], s[16:17], v0, s20, v[106:107]
	v_mov_b32_e32 v0, 0
	v_mad_i64_i32 v[126:127], s[22:23], v6, s20, v[100:101]
	v_mad_i64_i32 v[128:129], s[22:23], v6, s20, v[102:103]
	s_mov_b32 s21, 0
	s_mov_b64 s[16:17], 0
	v_mov_b32_e32 v1, v0
	v_mov_b32_e32 v2, v0
	v_mov_b32_e32 v3, v0
	v_mov_b32_e32 v4, v0
	v_mov_b32_e32 v5, v0
	v_mov_b32_e32 v6, v0
	v_mov_b32_e32 v7, v0
	v_mov_b32_e32 v8, v0
	v_mov_b32_e32 v9, v0
	v_mov_b32_e32 v10, v0
	v_mov_b32_e32 v11, v0
	v_mov_b32_e32 v12, v0
	v_mov_b32_e32 v13, v0
	v_mov_b32_e32 v14, v0
	v_mov_b32_e32 v15, v0
	v_mov_b32_e32 v16, v0
	v_mov_b32_e32 v17, v0
	v_mov_b32_e32 v18, v0
	v_mov_b32_e32 v19, v0
	v_mov_b32_e32 v20, v0
	v_mov_b32_e32 v21, v0
	v_mov_b32_e32 v22, v0
	v_mov_b32_e32 v23, v0
	v_mov_b32_e32 v24, v0
	v_mov_b32_e32 v25, v0
	v_mov_b32_e32 v26, v0
	v_mov_b32_e32 v27, v0
	v_mov_b32_e32 v28, v0
	v_mov_b32_e32 v29, v0
	v_mov_b32_e32 v30, v0
	v_mov_b32_e32 v31, v0
	v_mov_b32_e32 v32, v0
	v_mov_b32_e32 v33, v0
	v_mov_b32_e32 v34, v0
	v_mov_b32_e32 v35, v0
	v_mov_b32_e32 v36, v0
	v_mov_b32_e32 v37, v0
	v_mov_b32_e32 v38, v0
	v_mov_b32_e32 v39, v0
	v_mov_b32_e32 v40, v0
	v_mov_b32_e32 v41, v0
	v_mov_b32_e32 v42, v0
	v_mov_b32_e32 v43, v0
	v_mov_b32_e32 v44, v0
	v_mov_b32_e32 v45, v0
	v_mov_b32_e32 v46, v0
	v_mov_b32_e32 v47, v0
	v_mov_b32_e32 v48, v0
	v_mov_b32_e32 v49, v0
	v_mov_b32_e32 v50, v0
	v_mov_b32_e32 v51, v0
	v_mov_b32_e32 v52, v0
	v_mov_b32_e32 v53, v0
	v_mov_b32_e32 v54, v0
	v_mov_b32_e32 v55, v0
	v_mov_b32_e32 v56, v0
	v_mov_b32_e32 v57, v0
	v_mov_b32_e32 v58, v0
	v_mov_b32_e32 v59, v0
	v_mov_b32_e32 v60, v0
	v_mov_b32_e32 v61, v0
	v_mov_b32_e32 v62, v0
	v_mov_b32_e32 v63, v0
	v_mov_b32_e32 v64, v0
	v_mov_b32_e32 v65, v0
	v_mov_b32_e32 v66, v0
	v_mov_b32_e32 v67, v0
	v_mov_b32_e32 v68, v0
	v_mov_b32_e32 v69, v0
	v_mov_b32_e32 v70, v0
	v_mov_b32_e32 v71, v0
	v_mov_b32_e32 v72, v0
	v_mov_b32_e32 v73, v0
	v_mov_b32_e32 v74, v0
	v_mov_b32_e32 v75, v0
	v_mov_b32_e32 v76, v0
	v_mov_b32_e32 v77, v0
	v_mov_b32_e32 v78, v0
	v_mov_b32_e32 v79, v0
	.p2align 6
